# MIXIN q/k-head epilogue (norm gain + rope tables): each block's 4 gain loads and 4 cos/sin loads issued together (was 6 serial round trips per head block); on top of v40
# speedup vs baseline: 1.0096x; 1.0096x over previous
; template <int MI>
; __device__ __forceinline__ void epi_mixin(CParams& p, int j2, int m0, int tn, f32x4 (&acc)[MI][8]) {
;     ...
; #pragma unroll
;         for (int i = 0; i < MI; ++i) {
;             const int row = m0 + wave * 16 * MI + i * 16 + l16;
; #pragma unroll
;             for (int hh = 0; hh < 2; ++hh) {
;                 float ss = 0.f;
; #pragma unroll
;                 for (int j = 0; j < 4; ++j) { const f32x4 v = acc[i][hh * 4 + j]; ss += v[0] * v[0] + v[1] * v[1] + v[2] * v[2] + v[3] * v[3]; }
;                 ss += __shfl_xor(ss, 16); ss += __shfl_xor(ss, 32);
;                 const float rstd = rsqrtf(ss * (1.f / 64.f) + EPS);
;                 f32x4 y[4];
; #pragma unroll
;                 for (int j = 0; j < 4; ++j) {
;                     const f32x4 gv = *(const f32x4*)(gsrc + j * 16 + quad * 4);
;                     y[j] = acc[i][hh * 4 + j] * rstd * gv;
;                 }
;                 if (row < ML) {
;                     const int s = row & (SEQ - 1);
; #pragma unroll
;                     for (int j = 0; j < 2; ++j) {
;                         const f32x4 cs = *(const f32x4*)(cosT + (size_t)s * 32 + j * 16 + quad * 4);
;                         const f32x4 sn = *(const f32x4*)(sinT + (size_t)s * 32 + j * 16 + quad * 4);
;                         const f32x4 x1 = y[j], x2 = y[j + 2];
;                         y[j] = x1 * cs - x2 * sn;
;                         y[j + 2] = x2 * cs + x1 * sn;
;                     }
;                 }
.LBB0_138:
	s_andn2_b64 vcc, exec, s[4:5]
	s_cbranch_vccnz .LBB0_125
	s_cmp_lg_u32 s42, 4
	s_cselect_b64 s[8:9], -1, 0
	s_cmp_eq_u32 s42, 4
	s_movk_i32 s4, 0x68
	s_cselect_b32 s4, s4, 0x60
	v_readlane_b32 s6, v248, 24
	v_readlane_b32 s7, v248, 25
	s_add_u32 s4, s6, s4
	s_addc_u32 s5, s7, 0
	s_load_dwordx2 s[4:5], s[4:5], 0x0
	v_mov_b32_e32 v78, v61
	v_mov_b32_e32 v79, v57
	v_mov_b32_e32 v76, v60
	v_mov_b32_e32 v77, v56
	v_pk_mul_f32 v[78:79], v[78:79], v[78:79]
	v_mov_b32_e32 v80, v53
	v_pk_fma_f32 v[76:77], v[76:77], v[76:77], v[78:79]
	v_mov_b32_e32 v78, v62
	v_mov_b32_e32 v79, v58
	v_pk_fma_f32 v[76:77], v[78:79], v[78:79], v[76:77]
	v_mov_b32_e32 v78, v63
	v_mov_b32_e32 v79, v59
	v_mov_b32_e32 v81, v49
	v_pk_fma_f32 v[76:77], v[78:79], v[78:79], v[76:77]
	v_mov_b32_e32 v78, v52
	v_mov_b32_e32 v79, v48
	v_pk_mul_f32 v[80:81], v[80:81], v[80:81]
	s_waitcnt lgkmcnt(0)
	s_add_u32 s6, s4, s60
	v_pk_fma_f32 v[78:79], v[78:79], v[78:79], v[80:81]
	v_mov_b32_e32 v80, v54
	v_mov_b32_e32 v81, v50
	s_addc_u32 s7, s5, s61
	v_lshlrev_b32_e32 v74, 4, v158
	global_load_dwordx4 v[96:99], v74, s[6:7]
	global_load_dwordx4 v[100:103], v74, s[6:7] offset:64
	global_load_dwordx4 v[104:107], v74, s[6:7] offset:128
	global_load_dwordx4 v[108:111], v74, s[6:7] offset:192
	v_pk_fma_f32 v[78:79], v[80:81], v[80:81], v[78:79]
	v_mov_b32_e32 v80, v55
	v_mov_b32_e32 v81, v51
	v_pk_fma_f32 v[78:79], v[80:81], v[80:81], v[78:79]
	v_cmp_lt_i32_e32 vcc, v204, v199
	v_or_b32_e32 v64, s19, v160
	v_lshl_add_u32 v64, v159, 5, v64
	v_cndmask_b32_e32 v65, v197, v204, vcc
	v_cmp_lt_i32_e32 vcc, v205, v199
	v_lshlrev_b32_e32 v84, 2, v65
	v_mov_b32_e32 v75, v165
	v_cndmask_b32_e32 v65, v197, v205, vcc
	v_lshlrev_b32_e32 v85, 2, v65
	v_lshlrev_b32_e32 v65, 7, v64
	v_and_b32_e32 v164, 0xff780, v65
	v_add_f32_e32 v65, v76, v77
	v_add_f32_e32 v65, v65, v78
	v_add_f32_e32 v65, v65, v79
	ds_bpermute_b32 v76, v84, v65
	v_lshl_add_u64 v[66:67], s[52:53], 0, v[74:75]
	v_lshl_add_u64 v[68:69], s[54:55], 0, v[74:75]
	v_cmp_gt_i32_e64 s[44:45], s34, v64
	v_lshl_add_u64 v[72:73], v[66:67], 0, v[164:165]
	s_waitcnt lgkmcnt(0)
	v_add_f32_e32 v65, v65, v76
	ds_bpermute_b32 v76, v85, v65
	v_lshl_add_u64 v[70:71], v[68:69], 0, v[164:165]
	s_waitcnt lgkmcnt(0)
	v_add_f32_e32 v65, v65, v76
	v_fmamk_f32 v65, v65, 0x3c800000, v166
	v_cmp_gt_f32_e32 vcc, s41, v65
	v_mul_f32_e32 v76, 0x4b800000, v65
	s_nop 0
	v_cndmask_b32_e32 v65, v65, v76, vcc
	v_rsq_f32_e32 v65, v65
	s_nop 0
	v_mul_f32_e32 v76, 0x45800000, v65
	v_cndmask_b32_e32 v78, v65, v76, vcc
	v_pk_mul_f32 v[60:61], v[60:61], v[78:79] op_sel_hi:[1,0]
	v_pk_mul_f32 v[62:63], v[62:63], v[78:79] op_sel_hi:[1,0]
	v_pk_mul_f32 v[56:57], v[56:57], v[78:79] op_sel_hi:[1,0]
	v_pk_mul_f32 v[58:59], v[58:59], v[78:79] op_sel_hi:[1,0]
	v_pk_mul_f32 v[52:53], v[52:53], v[78:79] op_sel_hi:[1,0]
	v_pk_mul_f32 v[54:55], v[54:55], v[78:79] op_sel_hi:[1,0]
	s_waitcnt vmcnt(3)
	v_pk_mul_f32 v[82:83], v[98:99], v[62:63]
	v_pk_mul_f32 v[80:81], v[96:97], v[60:61]
	s_waitcnt vmcnt(2)
	v_pk_mul_f32 v[76:77], v[102:103], v[58:59]
	v_pk_mul_f32 v[62:63], v[100:101], v[56:57]
	s_waitcnt vmcnt(1)
	v_pk_mul_f32 v[58:59], v[106:107], v[54:55]
	v_pk_mul_f32 v[60:61], v[104:105], v[52:53]
	v_pk_mul_f32 v[56:57], v[48:49], v[78:79] op_sel_hi:[1,0]
	v_pk_mul_f32 v[48:49], v[50:51], v[78:79] op_sel_hi:[1,0]
	s_waitcnt vmcnt(0)
	v_pk_mul_f32 v[78:79], v[108:109], v[56:57]
	v_pk_mul_f32 v[48:49], v[110:111], v[48:49]
	v_mov_b32_e32 v52, v108
	v_mov_b32_e32 v53, v109
	v_mov_b32_e32 v54, v110
	v_mov_b32_e32 v55, v111
	s_and_saveexec_b64 s[4:5], s[44:45]
	s_cbranch_execz .LBB0_141
	global_load_dwordx4 v[96:99], v[72:73], off
	global_load_dwordx4 v[100:103], v[70:71], off
	global_load_dwordx4 v[104:107], v[72:73], off offset:64
	global_load_dwordx4 v[108:111], v[70:71], off offset:64
	s_waitcnt vmcnt(2)
	v_pk_mul_f32 v[86:87], v[58:59], v[102:103]
	v_pk_mul_f32 v[88:89], v[60:61], v[100:101]
	v_pk_mul_f32 v[56:57], v[82:83], v[102:103]
	v_pk_mul_f32 v[54:55], v[80:81], v[100:101]
	v_pk_fma_f32 v[86:87], v[82:83], v[98:99], v[86:87] neg_lo:[0,0,1] neg_hi:[0,0,1]
	v_pk_fma_f32 v[88:89], v[80:81], v[96:97], v[88:89] neg_lo:[0,0,1] neg_hi:[0,0,1]
	v_pk_fma_f32 v[58:59], v[58:59], v[98:99], v[56:57]
	v_pk_fma_f32 v[60:61], v[60:61], v[96:97], v[54:55]
	s_waitcnt vmcnt(0)
	v_pk_mul_f32 v[80:81], v[48:49], v[110:111]
	v_pk_mul_f32 v[82:83], v[78:79], v[108:109]
	v_pk_fma_f32 v[90:91], v[76:77], v[106:107], v[80:81] neg_lo:[0,0,1] neg_hi:[0,0,1]
	v_pk_fma_f32 v[92:93], v[62:63], v[104:105], v[82:83] neg_lo:[0,0,1] neg_hi:[0,0,1]
	v_pk_mul_f32 v[56:57], v[76:77], v[110:111]
	v_pk_mul_f32 v[54:55], v[62:63], v[108:109]
	v_pk_fma_f32 v[48:49], v[48:49], v[106:107], v[56:57]
	v_pk_fma_f32 v[78:79], v[78:79], v[104:105], v[54:55]
	v_mov_b32_e32 v80, v88
	v_mov_b32_e32 v81, v89
	v_mov_b32_e32 v82, v86
	v_mov_b32_e32 v83, v87
	v_mov_b32_e32 v62, v92
	v_mov_b32_e32 v63, v93
	v_mov_b32_e32 v76, v90
	v_mov_b32_e32 v77, v91
	v_mov_b32_e32 v50, v104
	v_mov_b32_e32 v51, v105
	v_mov_b32_e32 v52, v106
	v_mov_b32_e32 v53, v107

; template <int MI>
; __device__ __forceinline__ void epi_mixin(CParams& p, int j2, int m0, int tn, f32x4 (&acc)[MI][8]) {
;     ...
;             for (int hh = 0; hh < 2; ++hh) {
;                 float ss = 0.f;
; #pragma unroll
;                 for (int j = 0; j < 4; ++j) { const f32x4 v = acc[i][hh * 4 + j]; ss += v[0] * v[0] + v[1] * v[1] + v[2] * v[2] + v[3] * v[3]; }
;                 ss += __shfl_xor(ss, 16); ss += __shfl_xor(ss, 32);
;                 const float rstd = rsqrtf(ss * (1.f / 64.f) + EPS);
;                 f32x4 y[4];
; #pragma unroll
;                 for (int j = 0; j < 4; ++j) {
;                     const f32x4 gv = *(const f32x4*)(gsrc + j * 16 + quad * 4);
;                     y[j] = acc[i][hh * 4 + j] * rstd * gv;
;                 }
.LBB0_145:
	v_mov_b32_e32 v60, v45
	v_mov_b32_e32 v61, v41
	v_mov_b32_e32 v58, v44
	v_mov_b32_e32 v59, v40
	v_pk_mul_f32 v[60:61], v[60:61], v[60:61]
	v_mov_b32_e32 v62, v37
	v_pk_fma_f32 v[58:59], v[58:59], v[58:59], v[60:61]
	v_mov_b32_e32 v60, v46
	v_mov_b32_e32 v61, v42
	v_pk_fma_f32 v[58:59], v[60:61], v[60:61], v[58:59]
	v_mov_b32_e32 v60, v47
	v_mov_b32_e32 v61, v43
	v_mov_b32_e32 v63, v33
	v_pk_fma_f32 v[58:59], v[60:61], v[60:61], v[58:59]
	v_mov_b32_e32 v60, v36
	v_mov_b32_e32 v61, v32
	v_pk_mul_f32 v[62:63], v[62:63], v[62:63]
	v_add_f32_e32 v58, v58, v59
	v_pk_fma_f32 v[60:61], v[60:61], v[60:61], v[62:63]
	v_mov_b32_e32 v62, v38
	v_mov_b32_e32 v63, v34
	v_pk_fma_f32 v[60:61], v[62:63], v[62:63], v[60:61]
	v_mov_b32_e32 v62, v39
	v_mov_b32_e32 v63, v35
	v_pk_fma_f32 v[60:61], v[62:63], v[62:63], v[60:61]
	v_lshl_add_u64 v[48:49], s[6:7], 0, v[74:75]
	global_load_dwordx4 v[96:99], v[48:49], off
	global_load_dwordx4 v[100:103], v[48:49], off offset:64
	global_load_dwordx4 v[104:107], v[48:49], off offset:128
	global_load_dwordx4 v[108:111], v[48:49], off offset:192
	v_add_f32_e32 v58, v58, v60
	v_add_f32_e32 v58, v58, v61
	ds_bpermute_b32 v59, v84, v58
	s_waitcnt lgkmcnt(0)
	v_add_f32_e32 v58, v58, v59
	ds_bpermute_b32 v59, v85, v58
	s_waitcnt lgkmcnt(0)
	v_add_f32_e32 v58, v58, v59
	v_fmamk_f32 v58, v58, 0x3c800000, v166
	v_cmp_gt_f32_e32 vcc, s41, v58
	v_mul_f32_e32 v59, 0x4b800000, v58
	s_nop 0
	v_cndmask_b32_e32 v58, v58, v59, vcc
	v_rsq_f32_e32 v58, v58
	s_nop 0
	v_mul_f32_e32 v59, 0x45800000, v58
	v_cndmask_b32_e32 v58, v58, v59, vcc
	v_pk_mul_f32 v[44:45], v[44:45], v[58:59] op_sel_hi:[1,0]
	v_pk_mul_f32 v[46:47], v[46:47], v[58:59] op_sel_hi:[1,0]
	v_pk_mul_f32 v[40:41], v[40:41], v[58:59] op_sel_hi:[1,0]
	v_pk_mul_f32 v[42:43], v[42:43], v[58:59] op_sel_hi:[1,0]
	v_pk_mul_f32 v[74:75], v[36:37], v[58:59] op_sel_hi:[1,0]
	v_pk_mul_f32 v[36:37], v[38:39], v[58:59] op_sel_hi:[1,0]
	s_waitcnt vmcnt(3)
	v_pk_mul_f32 v[46:47], v[98:99], v[46:47]
	v_pk_mul_f32 v[44:45], v[96:97], v[44:45]
	s_waitcnt vmcnt(2)
	v_pk_mul_f32 v[42:43], v[102:103], v[42:43]
	v_pk_mul_f32 v[40:41], v[100:101], v[40:41]
	s_waitcnt vmcnt(1)
	v_pk_mul_f32 v[36:37], v[106:107], v[36:37]
	v_pk_mul_f32 v[38:39], v[104:105], v[74:75]
	v_pk_mul_f32 v[74:75], v[32:33], v[58:59] op_sel_hi:[1,0]
	v_pk_mul_f32 v[32:33], v[34:35], v[58:59] op_sel_hi:[1,0]
	s_waitcnt vmcnt(0)
	v_pk_mul_f32 v[34:35], v[108:109], v[74:75]
	v_pk_mul_f32 v[32:33], v[110:111], v[32:33]
	v_mov_b32_e32 v60, v108
	v_mov_b32_e32 v61, v109
	v_mov_b32_e32 v62, v110
	v_mov_b32_e32 v63, v111
	s_and_saveexec_b64 s[6:7], s[44:45]
	s_cbranch_execnz .LBB0_158
	s_or_b64 exec, exec, s[6:7]
	s_and_b64 vcc, exec, s[42:43]
	s_mov_b64 s[6:7], -1
	s_cbranch_vccz .LBB0_159

; template <int MI>
; __device__ __forceinline__ void epi_mixin(CParams& p, int j2, int m0, int tn, f32x4 (&acc)[MI][8]) {
;     ...
; #pragma unroll
;         for (int i = 0; i < MI; ++i) {
;             const int row = m0 + wave * 16 * MI + i * 16 + l16;
; #pragma unroll
;             for (int hh = 0; hh < 2; ++hh) {
;                 float ss = 0.f;
; #pragma unroll
;                 for (int j = 0; j < 4; ++j) { const f32x4 v = acc[i][hh * 4 + j]; ss += v[0] * v[0] + v[1] * v[1] + v[2] * v[2] + v[3] * v[3]; }
;                 ss += __shfl_xor(ss, 16); ss += __shfl_xor(ss, 32);
;                 const float rstd = rsqrtf(ss * (1.f / 64.f) + EPS);
;                 f32x4 y[4];
; #pragma unroll
;                 for (int j = 0; j < 4; ++j) {
;                     const f32x4 gv = *(const f32x4*)(gsrc + j * 16 + quad * 4);
;                     y[j] = acc[i][hh * 4 + j] * rstd * gv;
;                 }
;                 if (row < ML) {
;                     const int s = row & (SEQ - 1);
; #pragma unroll
;                     for (int j = 0; j < 2; ++j) {
;                         const f32x4 cs = *(const f32x4*)(cosT + (size_t)s * 32 + j * 16 + quad * 4);
;                         const f32x4 sn = *(const f32x4*)(sinT + (size_t)s * 32 + j * 16 + quad * 4);
;                         const f32x4 x1 = y[j], x2 = y[j + 2];
;                         y[j] = x1 * cs - x2 * sn;
;                         y[j + 2] = x2 * cs + x1 * sn;
;                     }
;                 }
.LBB0_149:
	global_load_dwordx4 v[96:99], v[48:49], off
	global_load_dwordx4 v[100:103], v[48:49], off offset:64
	global_load_dwordx4 v[104:107], v[48:49], off offset:128
	global_load_dwordx4 v[108:111], v[48:49], off offset:192
	v_mov_b32_e32 v40, v29
	v_mov_b32_e32 v41, v25
	v_mov_b32_e32 v38, v28
	v_mov_b32_e32 v39, v24
	v_pk_mul_f32 v[40:41], v[40:41], v[40:41]
	v_mov_b32_e32 v42, v21
	v_pk_fma_f32 v[38:39], v[38:39], v[38:39], v[40:41]
	v_mov_b32_e32 v40, v30
	v_mov_b32_e32 v41, v26
	v_pk_fma_f32 v[38:39], v[40:41], v[40:41], v[38:39]
	v_mov_b32_e32 v40, v31
	v_mov_b32_e32 v41, v27
	v_mov_b32_e32 v43, v17
	v_pk_fma_f32 v[38:39], v[40:41], v[40:41], v[38:39]
	v_mov_b32_e32 v40, v20
	v_mov_b32_e32 v41, v16
	v_pk_mul_f32 v[42:43], v[42:43], v[42:43]
	v_add_f32_e32 v37, v38, v39
	v_pk_fma_f32 v[40:41], v[40:41], v[40:41], v[42:43]
	v_mov_b32_e32 v42, v22
	v_mov_b32_e32 v43, v18
	v_pk_fma_f32 v[40:41], v[42:43], v[42:43], v[40:41]
	v_mov_b32_e32 v42, v23
	v_mov_b32_e32 v43, v19
	v_pk_fma_f32 v[40:41], v[42:43], v[42:43], v[40:41]
	v_or_b32_e32 v36, 16, v64
	v_add_f32_e32 v37, v37, v40
	v_add_f32_e32 v37, v37, v41
	ds_bpermute_b32 v38, v84, v37
	v_lshlrev_b32_e32 v32, 7, v36
	v_and_b32_e32 v164, 0xfff80, v32
	v_cmp_gt_i32_e64 s[44:45], s34, v36
	v_lshl_add_u64 v[34:35], v[66:67], 0, v[164:165]
	s_waitcnt lgkmcnt(0)
	v_add_f32_e32 v37, v37, v38
	ds_bpermute_b32 v38, v85, v37
	v_lshl_add_u64 v[32:33], v[68:69], 0, v[164:165]
	s_waitcnt lgkmcnt(0)
	v_add_f32_e32 v37, v37, v38
	v_fmamk_f32 v37, v37, 0x3c800000, v166
	v_cmp_gt_f32_e32 vcc, s41, v37
	v_mul_f32_e32 v38, 0x4b800000, v37
	s_nop 0
	v_cndmask_b32_e32 v37, v37, v38, vcc
	v_rsq_f32_e32 v37, v37
	s_nop 0
	v_mul_f32_e32 v38, 0x45800000, v37
	v_cndmask_b32_e32 v38, v37, v38, vcc
	v_pk_mul_f32 v[28:29], v[28:29], v[38:39] op_sel_hi:[1,0]
	v_pk_mul_f32 v[30:31], v[30:31], v[38:39] op_sel_hi:[1,0]
	v_pk_mul_f32 v[24:25], v[24:25], v[38:39] op_sel_hi:[1,0]
	v_pk_mul_f32 v[26:27], v[26:27], v[38:39] op_sel_hi:[1,0]
	v_pk_mul_f32 v[44:45], v[20:21], v[38:39] op_sel_hi:[1,0]
	v_pk_mul_f32 v[20:21], v[22:23], v[38:39] op_sel_hi:[1,0]
	v_pk_mul_f32 v[16:17], v[16:17], v[38:39] op_sel_hi:[1,0]
	v_pk_mul_f32 v[18:19], v[18:19], v[38:39] op_sel_hi:[1,0]
	s_waitcnt vmcnt(3)
	v_pk_mul_f32 v[30:31], v[98:99], v[30:31]
	v_pk_mul_f32 v[28:29], v[96:97], v[28:29]
	s_waitcnt vmcnt(2)
	v_pk_mul_f32 v[26:27], v[102:103], v[26:27]
	v_pk_mul_f32 v[24:25], v[100:101], v[24:25]
	s_waitcnt vmcnt(1)
	v_pk_mul_f32 v[20:21], v[106:107], v[20:21]
	v_pk_mul_f32 v[22:23], v[104:105], v[44:45]
	s_waitcnt vmcnt(0)
	v_pk_mul_f32 v[38:39], v[110:111], v[18:19]
	v_pk_mul_f32 v[40:41], v[108:109], v[16:17]
	v_mov_b32_e32 v42, v110
	v_mov_b32_e32 v43, v111
	s_and_saveexec_b64 s[6:7], s[44:45]
	s_cbranch_execz .LBB0_151
	global_load_dwordx4 v[96:99], v[34:35], off
	global_load_dwordx4 v[100:103], v[32:33], off
	global_load_dwordx4 v[104:107], v[34:35], off offset:64
	global_load_dwordx4 v[108:111], v[32:33], off offset:64
	s_waitcnt vmcnt(2)
	v_pk_mul_f32 v[46:47], v[20:21], v[102:103]
	v_pk_mul_f32 v[54:55], v[22:23], v[100:101]
	v_pk_fma_f32 v[46:47], v[30:31], v[98:99], v[46:47] neg_lo:[0,0,1] neg_hi:[0,0,1]
	v_pk_fma_f32 v[54:55], v[28:29], v[96:97], v[54:55] neg_lo:[0,0,1] neg_hi:[0,0,1]
	v_pk_mul_f32 v[30:31], v[30:31], v[102:103]
	v_pk_mul_f32 v[28:29], v[28:29], v[100:101]
	v_pk_fma_f32 v[20:21], v[20:21], v[98:99], v[30:31]
	v_pk_fma_f32 v[22:23], v[22:23], v[96:97], v[28:29]
	s_waitcnt vmcnt(0)
	v_pk_mul_f32 v[42:43], v[38:39], v[110:111]
	v_pk_mul_f32 v[44:45], v[40:41], v[108:109]
	v_pk_fma_f32 v[42:43], v[26:27], v[106:107], v[42:43] neg_lo:[0,0,1] neg_hi:[0,0,1]
	v_pk_fma_f32 v[44:45], v[24:25], v[104:105], v[44:45] neg_lo:[0,0,1] neg_hi:[0,0,1]
	v_pk_mul_f32 v[26:27], v[26:27], v[110:111]
	v_pk_mul_f32 v[24:25], v[24:25], v[108:109]
	v_pk_fma_f32 v[38:39], v[38:39], v[106:107], v[26:27]
	v_pk_fma_f32 v[40:41], v[40:41], v[104:105], v[24:25]
	v_mov_b32_e32 v28, v54
	v_mov_b32_e32 v29, v55
	v_mov_b32_e32 v30, v46
	v_mov_b32_e32 v31, v47
	v_mov_b32_e32 v24, v44
	v_mov_b32_e32 v25, v45
	v_mov_b32_e32 v26, v42
	v_mov_b32_e32 v27, v43
	v_mov_b32_e32 v16, v104
	v_mov_b32_e32 v17, v105
	v_mov_b32_e32 v18, v106
	v_mov_b32_e32 v19, v107

; template <int MI>
; __device__ __forceinline__ void epi_mixin(CParams& p, int j2, int m0, int tn, f32x4 (&acc)[MI][8]) {
;     ...
;             for (int hh = 0; hh < 2; ++hh) {
;                 float ss = 0.f;
; #pragma unroll
;                 for (int j = 0; j < 4; ++j) { const f32x4 v = acc[i][hh * 4 + j]; ss += v[0] * v[0] + v[1] * v[1] + v[2] * v[2] + v[3] * v[3]; }
;                 ss += __shfl_xor(ss, 16); ss += __shfl_xor(ss, 32);
;                 const float rstd = rsqrtf(ss * (1.f / 64.f) + EPS);
;                 f32x4 y[4];
; #pragma unroll
;                 for (int j = 0; j < 4; ++j) {
;                     const f32x4 gv = *(const f32x4*)(gsrc + j * 16 + quad * 4);
;                     y[j] = acc[i][hh * 4 + j] * rstd * gv;
;                 }
.LBB0_155:
	global_load_dwordx4 v[96:99], v[48:49], off
	global_load_dwordx4 v[100:103], v[48:49], off offset:64
	global_load_dwordx4 v[104:107], v[48:49], off offset:128
	global_load_dwordx4 v[108:111], v[48:49], off offset:192
	v_mov_b32_e32 v22, v13
	v_mov_b32_e32 v23, v9
	v_mov_b32_e32 v20, v12
	v_mov_b32_e32 v21, v8
	v_pk_mul_f32 v[22:23], v[22:23], v[22:23]
	v_mov_b32_e32 v24, v5
	v_pk_fma_f32 v[20:21], v[20:21], v[20:21], v[22:23]
	v_mov_b32_e32 v22, v14
	v_mov_b32_e32 v23, v10
	v_pk_fma_f32 v[20:21], v[22:23], v[22:23], v[20:21]
	v_mov_b32_e32 v22, v15
	v_mov_b32_e32 v23, v11
	v_mov_b32_e32 v25, v1
	v_pk_fma_f32 v[20:21], v[22:23], v[22:23], v[20:21]
	v_mov_b32_e32 v22, v4
	v_mov_b32_e32 v23, v0
	v_pk_mul_f32 v[24:25], v[24:25], v[24:25]
	v_add_f32_e32 v20, v20, v21
	v_pk_fma_f32 v[22:23], v[22:23], v[22:23], v[24:25]
	v_mov_b32_e32 v24, v6
	v_mov_b32_e32 v25, v2
	v_pk_fma_f32 v[22:23], v[24:25], v[24:25], v[22:23]
	v_mov_b32_e32 v24, v7
	v_mov_b32_e32 v25, v3
	v_pk_fma_f32 v[22:23], v[24:25], v[24:25], v[22:23]
	s_nop 0
	v_add_f32_e32 v20, v20, v22
	v_add_f32_e32 v20, v20, v23
	ds_bpermute_b32 v21, v84, v20
	s_waitcnt lgkmcnt(0)
	v_add_f32_e32 v20, v20, v21
	ds_bpermute_b32 v21, v85, v20
	s_waitcnt lgkmcnt(0)
	v_add_f32_e32 v20, v20, v21
	v_fmamk_f32 v20, v20, 0x3c800000, v166
	v_cmp_gt_f32_e32 vcc, s41, v20
	v_mul_f32_e32 v21, 0x4b800000, v20
	s_nop 0
	v_cndmask_b32_e32 v20, v20, v21, vcc
	v_rsq_f32_e32 v20, v20
	s_nop 0
	v_mul_f32_e32 v21, 0x45800000, v20
	v_cndmask_b32_e32 v20, v20, v21, vcc
	v_pk_mul_f32 v[12:13], v[12:13], v[20:21] op_sel_hi:[1,0]
	v_pk_mul_f32 v[14:15], v[14:15], v[20:21] op_sel_hi:[1,0]
	v_pk_mul_f32 v[8:9], v[8:9], v[20:21] op_sel_hi:[1,0]
	v_pk_mul_f32 v[10:11], v[10:11], v[20:21] op_sel_hi:[1,0]
	v_pk_mul_f32 v[26:27], v[4:5], v[20:21] op_sel_hi:[1,0]
	v_pk_mul_f32 v[4:5], v[6:7], v[20:21] op_sel_hi:[1,0]
	s_waitcnt vmcnt(3)
	v_pk_mul_f32 v[14:15], v[98:99], v[14:15]
	v_pk_mul_f32 v[12:13], v[96:97], v[12:13]
	s_waitcnt vmcnt(2)
	v_pk_mul_f32 v[10:11], v[102:103], v[10:11]
	v_pk_mul_f32 v[8:9], v[100:101], v[8:9]
	s_waitcnt vmcnt(1)
	v_pk_mul_f32 v[4:5], v[106:107], v[4:5]
	v_pk_mul_f32 v[6:7], v[104:105], v[26:27]
	v_pk_mul_f32 v[26:27], v[0:1], v[20:21] op_sel_hi:[1,0]
	v_pk_mul_f32 v[0:1], v[2:3], v[20:21] op_sel_hi:[1,0]
	s_waitcnt vmcnt(0)
	v_pk_mul_f32 v[2:3], v[108:109], v[26:27]
	v_pk_mul_f32 v[0:1], v[110:111], v[0:1]
	v_mov_b32_e32 v22, v108
	v_mov_b32_e32 v23, v109
	v_mov_b32_e32 v24, v110
	v_mov_b32_e32 v25, v111
	s_and_saveexec_b64 s[6:7], s[44:45]
	s_cbranch_execnz .LBB0_160
	s_or_b64 exec, exec, s[6:7]
	s_and_b64 vcc, exec, s[42:43]
	s_mov_b64 s[6:7], -1
	s_cbranch_vccz .LBB0_161
